# SSD prompt loop: y stores deferred past next chunk B1, all prefetch loads issued by B2
# speedup vs baseline: 1.0331x; 1.0047x over previous
.LBB0_1067:
	global_store_dwordx2 v[248:249], v[240:241], off
	global_store_dwordx2 v[248:249], v[242:243], off offset:32
	global_store_dwordx2 v[248:249], v[244:245], off offset:64
	global_store_dwordx2 v[248:249], v[246:247], off offset:96
	v_readlane_b32 s0, v254, 37
	v_readlane_b32 s1, v254, 38
	s_ashr_i32 s1, s0, 31
	s_lshl_b64 s[0:1], s[0:1], 15
	v_readlane_b32 s2, v253, 20
	s_add_u32 s2, s2, s0
	v_readlane_b32 s0, v253, 21
	s_addc_u32 s3, s0, s1
	v_readlane_b32 s0, v253, 51
	v_readlane_b32 s1, v253, 52
	s_ashr_i32 s1, s0, 31
	s_lshl_b64 s[0:1], s[0:1], 2
	s_add_u32 s0, s2, s0
	s_addc_u32 s1, s3, s1
	v_lshlrev_b32_e32 v186, 2, v178
	s_waitcnt vmcnt(17)
	v_lshl_add_u64 v[4:5], s[0:1], 0, v[186:187]
	v_lshlrev_b32_e32 v186, 9, v165
	v_lshl_add_u64 v[4:5], v[4:5], 0, v[186:187]
	v_add_co_u32_e32 v6, vcc, 0x2000, v4
	v_readlane_b32 s0, v251, 0
	s_nop 0
	v_addc_co_u32_e32 v7, vcc, 0, v5, vcc
	global_store_dwordx4 v[6:7], v[64:67], off
	v_add_co_u32_e32 v6, vcc, 0x4000, v4
	v_readlane_b32 s36, v252, 48
	s_nop 0
	v_addc_co_u32_e32 v7, vcc, 0, v5, vcc
	v_readlane_b32 s6, v251, 6
	v_readlane_b32 s7, v251, 7
	v_readlane_b32 s42, v252, 54
	v_readlane_b32 s43, v252, 55
	v_readlane_b32 s48, v252, 60
	v_readlane_b32 s49, v252, 61
	v_readlane_b32 s50, v252, 62
	v_readlane_b32 s51, v252, 63
	global_store_dwordx4 v[4:5], v[60:63], off
	v_add_co_u32_e32 v4, vcc, 0x6000, v4
	v_readlane_b32 s1, v251, 1
	v_readlane_b32 s2, v251, 2
	v_readlane_b32 s3, v251, 3
	v_readlane_b32 s4, v251, 4
	v_readlane_b32 s5, v251, 5
	v_readlane_b32 s34, v253, 34
	s_mov_b64 s[54:55], s[6:7]
	v_readlane_b32 s42, v251, 37
	v_readlane_b32 s56, v253, 36
	v_addc_co_u32_e32 v5, vcc, 0, v5, vcc
	v_readlane_b32 s35, v253, 35
	v_readlane_b32 s37, v252, 49
	v_readlane_b32 s38, v252, 50
	v_readlane_b32 s39, v252, 51
	v_readlane_b32 s40, v252, 52
	v_readlane_b32 s41, v252, 53
	s_mov_b64 s[52:53], s[4:5]
	s_mov_b64 s[50:51], s[2:3]
	s_mov_b64 s[48:49], s[0:1]
	v_readlane_b32 s43, v251, 38
	v_readlane_b32 s57, v253, 37
	v_readlane_b32 s76, v253, 38
	s_movk_i32 s77, 0x2600
	s_movk_i32 s78, 0x1000
	s_movk_i32 s79, 0x2000
	global_store_dwordx4 v[6:7], v[68:71], off
	global_store_dwordx4 v[4:5], v[72:75], off
	v_readlane_b32 s44, v252, 56
	v_readlane_b32 s45, v252, 57
	v_readlane_b32 s46, v252, 58
	v_readlane_b32 s47, v252, 59

.LBB0_1188:
	v_add_u32_e32 v92, s80, v167
	s_movk_i32 s68, 0xc00
	v_cvt_pk_bf16_f32 v240, v76, v77
	v_cvt_pk_bf16_f32 v241, v78, v79
	v_mad_i64_i32 v[248:249], s[68:69], v92, s68, v[158:159]
	v_cvt_pk_bf16_f32 v242, v80, v81
	v_cvt_pk_bf16_f32 v243, v82, v83
	v_cvt_pk_bf16_f32 v244, v84, v85
	v_cvt_pk_bf16_f32 v245, v86, v87
	v_cvt_pk_bf16_f32 v246, v88, v89
	v_cvt_pk_bf16_f32 v247, v90, v91
	v_mul_f32_e32 v76, 0x3fb8aa3b, v236
	v_exp_f32_e32 v76, v76
	s_add_i32 s74, s74, 1
	s_addk_i32 s80, 0x80
	s_cmpk_lg_i32 s80, 0x800
	v_pk_mul_f32 v[62:63], v[62:63], v[76:77] op_sel_hi:[1,0]
	v_pk_mul_f32 v[60:61], v[60:61], v[76:77] op_sel_hi:[1,0]
	v_pk_mul_f32 v[66:67], v[66:67], v[76:77] op_sel_hi:[1,0]
	v_pk_mul_f32 v[64:65], v[64:65], v[76:77] op_sel_hi:[1,0]
	v_pk_mul_f32 v[70:71], v[70:71], v[76:77] op_sel_hi:[1,0]
	v_pk_mul_f32 v[68:69], v[68:69], v[76:77] op_sel_hi:[1,0]
	v_pk_mul_f32 v[74:75], v[74:75], v[76:77] op_sel_hi:[1,0]
	v_pk_mul_f32 v[72:73], v[72:73], v[76:77] op_sel_hi:[1,0]
	v_add_u32_e32 v136, v211, v207
	v_add_u32_e32 v137, v211, v209
	v_add_u32_e32 v138, v211, v210
	ds_read_b128 v[76:79], v230
	ds_read_b128 v[80:83], v231
	ds_read_b128 v[84:87], v231 offset:4352
	ds_read_b128 v[88:91], v231 offset:8704
	ds_read_b128 v[92:95], v231 offset:13056
	ds_read_b128 v[96:99], v230 offset:64
	ds_read_b128 v[100:103], v136
	ds_read_b128 v[104:107], v232 offset:4352
	ds_read_b128 v[108:111], v232 offset:8704
	ds_read_b128 v[112:115], v232 offset:13056
	ds_read_b128 v[116:119], v230 offset:128
	ds_read_b128 v[120:123], v137
	ds_read_b128 v[124:127], v233 offset:4352
	ds_read_b128 v[128:131], v233 offset:8704
	ds_read_b128 v[132:135], v233 offset:13056
	s_waitcnt lgkmcnt(13)
	v_mfma_f32_16x16x32_bf16 v[60:63], v[76:79], v[80:83], v[60:63]
	s_waitcnt lgkmcnt(12)
	v_mfma_f32_16x16x32_bf16 v[64:67], v[76:79], v[84:87], v[64:67]
	s_waitcnt lgkmcnt(11)
	v_mfma_f32_16x16x32_bf16 v[68:71], v[76:79], v[88:91], v[68:71]
	s_waitcnt lgkmcnt(10)
	v_mfma_f32_16x16x32_bf16 v[72:75], v[76:79], v[92:95], v[72:75]
	ds_read_b128 v[76:79], v230 offset:192
	ds_read_b128 v[80:83], v138
	ds_read_b128 v[84:87], v234 offset:4352
	ds_read_b128 v[88:91], v234 offset:8704
	ds_read_b128 v[92:95], v234 offset:13056
	s_waitcnt lgkmcnt(13)
	v_mfma_f32_16x16x32_bf16 v[60:63], v[96:99], v[100:103], v[60:63]
	s_waitcnt lgkmcnt(12)
	v_mfma_f32_16x16x32_bf16 v[64:67], v[96:99], v[104:107], v[64:67]
	s_waitcnt lgkmcnt(11)
	v_mfma_f32_16x16x32_bf16 v[68:71], v[96:99], v[108:111], v[68:71]
	s_waitcnt lgkmcnt(10)
	v_mfma_f32_16x16x32_bf16 v[72:75], v[96:99], v[112:115], v[72:75]
	s_waitcnt lgkmcnt(8)
	v_mfma_f32_16x16x32_bf16 v[60:63], v[116:119], v[120:123], v[60:63]
	s_waitcnt lgkmcnt(7)
	v_mfma_f32_16x16x32_bf16 v[64:67], v[116:119], v[124:127], v[64:67]
	s_waitcnt lgkmcnt(6)
	v_mfma_f32_16x16x32_bf16 v[68:71], v[116:119], v[128:131], v[68:71]
	s_waitcnt lgkmcnt(5)
	v_mfma_f32_16x16x32_bf16 v[72:75], v[116:119], v[132:135], v[72:75]
	s_waitcnt lgkmcnt(3)
	v_mfma_f32_16x16x32_bf16 v[60:63], v[76:79], v[80:83], v[60:63]
	s_waitcnt lgkmcnt(2)
	v_mfma_f32_16x16x32_bf16 v[64:67], v[76:79], v[84:87], v[64:67]
	s_waitcnt lgkmcnt(1)
	v_mfma_f32_16x16x32_bf16 v[68:71], v[76:79], v[88:91], v[68:71]
	s_waitcnt lgkmcnt(0)
	v_mfma_f32_16x16x32_bf16 v[72:75], v[76:79], v[92:95], v[72:75]
	s_nop 3
	v_cvt_pk_bf16_f32 v76, v60, v61
	v_cvt_pk_bf16_f32 v77, v62, v63
	ds_write_b64 v235, v[76:77]
	v_cvt_pk_bf16_f32 v76, v64, v65
	v_cvt_pk_bf16_f32 v77, v66, v67
	ds_write_b64 v235, v[76:77] offset:4352
	v_cvt_pk_bf16_f32 v76, v68, v69
	v_cvt_pk_bf16_f32 v77, v70, v71
	ds_write_b64 v235, v[76:77] offset:8704
	v_cvt_pk_bf16_f32 v76, v72, v73
	v_cvt_pk_bf16_f32 v77, v74, v75
	ds_write_b64 v235, v[76:77] offset:13056
	s_waitcnt lgkmcnt(0)
	s_barrier
	s_cbranch_scc0 .LBB0_1067

.LBB0_1191:
	s_waitcnt lgkmcnt(0)
	v_sub_f32_e32 v78, v236, v78
	v_sub_f32_e32 v79, v236, v79
	v_mul_f32_e32 v78, 0x3fb8aa3b, v78
	v_mul_f32_e32 v79, 0x3fb8aa3b, v79
	v_exp_f32_e32 v78, v78
	v_exp_f32_e32 v79, v79
	s_waitcnt vmcnt(1)
	v_lshlrev_b32_e32 v90, 16, v55
	v_and_b32_e32 v91, 0xffff0000, v55
	v_mul_f32_e32 v76, v76, v78
	v_mul_f32_e32 v77, v77, v79
	ds_bpermute_b32 v78, v183, v76
	ds_bpermute_b32 v79, v183, v77
	ds_bpermute_b32 v80, v186, v76
	ds_bpermute_b32 v81, v186, v77
	ds_bpermute_b32 v82, v188, v76
	ds_bpermute_b32 v83, v188, v77
	s_waitcnt lgkmcnt(4)
	v_cndmask_b32_e64 v84, v79, v78, s[18:19]
	ds_bpermute_b32 v78, v189, v76
	s_waitcnt lgkmcnt(3)
	v_cndmask_b32_e64 v80, v81, v80, s[18:19]
	ds_bpermute_b32 v79, v189, v77
	s_waitcnt lgkmcnt(2)
	v_cndmask_b32_e64 v81, v83, v82, s[18:19]
	ds_bpermute_b32 v82, v190, v76
	ds_bpermute_b32 v83, v190, v77
	ds_bpermute_b32 v85, v191, v76
	ds_bpermute_b32 v86, v191, v77
	ds_bpermute_b32 v87, v192, v76
	ds_bpermute_b32 v88, v192, v77
	ds_bpermute_b32 v76, v193, v76
	ds_bpermute_b32 v77, v193, v77
	s_waitcnt lgkmcnt(6)
	v_cndmask_b32_e64 v82, v83, v82, s[18:19]
	s_waitcnt lgkmcnt(4)
	v_cndmask_b32_e64 v83, v86, v85, s[18:19]
	v_cndmask_b32_e64 v89, v79, v78, s[18:19]
	v_lshlrev_b32_e32 v78, 16, v53
	s_waitcnt lgkmcnt(0)
	v_cndmask_b32_e64 v86, v77, v76, s[18:19]
	v_lshlrev_b32_e32 v76, 16, v52
	v_and_b32_e32 v77, 0xffff0000, v52
	v_and_b32_e32 v79, 0xffff0000, v53
	v_mul_f32_e32 v76, v76, v84
	v_mul_f32_e32 v77, v77, v80
	v_cndmask_b32_e64 v85, v88, v87, s[18:19]
	v_lshlrev_b32_e32 v87, 16, v54
	v_and_b32_e32 v88, 0xffff0000, v54
	v_cvt_pk_bf16_f32 v76, v76, v77
	v_mul_f32_e32 v77, v78, v81
	v_mul_f32_e32 v78, v79, v89
	v_cvt_pk_bf16_f32 v77, v77, v78
	v_mul_f32_e32 v78, v87, v82
	v_mul_f32_e32 v79, v88, v83
	v_cvt_pk_bf16_f32 v78, v78, v79
	v_mul_f32_e32 v79, v90, v85
	ds_write_b128 v213, v[8:11]
	ds_write_b128 v213, v[4:7] offset:34816
	ds_write_b128 v214, v[12:15]
	ds_write_b128 v213, v[20:23] offset:8704
	ds_write_b128 v213, v[16:19] offset:43520
	ds_write_b128 v214, v[24:27] offset:8704
	ds_write_b128 v213, v[28:31] offset:17408
	ds_write_b128 v213, v[32:35] offset:52224
	ds_write_b128 v214, v[36:39] offset:17408
	ds_write_b128 v213, v[44:47] offset:26112
	ds_write_b128 v213, v[40:43] offset:60928
	ds_write_b128 v214, v[48:51] offset:26112
	v_mul_f32_e32 v87, v91, v86
	v_cvt_pk_bf16_f32 v79, v79, v87
	ds_write_b128 v216, v[76:79]
	s_waitcnt vmcnt(0)
	v_lshlrev_b32_e32 v76, 16, v56
	v_and_b32_e32 v77, 0xffff0000, v56
	v_lshlrev_b32_e32 v78, 16, v57
	v_and_b32_e32 v79, 0xffff0000, v57
	v_mul_f32_e32 v76, v76, v84
	v_mul_f32_e32 v77, v77, v80
	v_lshlrev_b32_e32 v87, 16, v58
	v_and_b32_e32 v88, 0xffff0000, v58
	v_cvt_pk_bf16_f32 v76, v76, v77
	v_mul_f32_e32 v77, v78, v81
	v_mul_f32_e32 v78, v79, v89
	v_lshlrev_b32_e32 v90, 16, v59
	v_cvt_pk_bf16_f32 v77, v77, v78
	v_mul_f32_e32 v78, v87, v82
	v_mul_f32_e32 v79, v88, v83
	v_and_b32_e32 v91, 0xffff0000, v59
	v_cvt_pk_bf16_f32 v78, v78, v79
	v_mul_f32_e32 v79, v90, v85
	ds_write_b128 v215, v[52:55]
	ds_write_b128 v215, v[56:59] offset:8704
	v_mul_f32_e32 v80, v91, v86
	v_cvt_pk_bf16_f32 v79, v79, v80
	ds_write_b128 v216, v[76:79] offset:8704
	s_waitcnt lgkmcnt(0)
	s_barrier
	s_cmp_eq_u32 s80, 0
	s_cbranch_scc1 .Lssd_ys_skip
	global_store_dwordx2 v[248:249], v[240:241], off
	global_store_dwordx2 v[248:249], v[242:243], off offset:32
	global_store_dwordx2 v[248:249], v[244:245], off offset:64
	global_store_dwordx2 v[248:249], v[246:247], off offset:96
.Lssd_ys_skip:
	s_cmpk_eq_i32 s80, 0x780
	s_cbranch_scc1 .LBB0_1193
	v_add_u32_e32 v8, s80, v166
	v_add_u32_e32 v6, 0x80, v8
	v_mov_b64_e32 v[4:5], s[86:87]
	s_movk_i32 s75, 0x60
	v_add_u32_e32 v8, 0xc0, v8
	v_mad_i64_i32 v[6:7], s[68:69], v6, s75, v[4:5]
	v_mad_i64_i32 v[4:5], s[68:69], v8, s75, v[4:5]
	s_ashr_i32 s75, s74, 31
	s_lshl_b64 s[68:69], s[74:75], 17
	s_mul_i32 s76, s74, 24
	s_mul_hi_i32 s75, s74, 24
	s_add_u32 s76, s76, s82
	v_add_u32_e32 v40, s80, v142
	s_addc_u32 s77, s75, s83
	v_add_u32_e32 v8, 0x80, v40
	v_add_u32_e32 v16, 0xa0, v40
	v_add_u32_e32 v26, 0xc0, v40
	v_add_u32_e32 v40, 0xe0, v40
	v_lshl_add_u64 v[48:49], v[146:147], 0, s[68:69]
	v_ashrrev_i32_e32 v9, 31, v8
	v_ashrrev_i32_e32 v17, 31, v16
	v_ashrrev_i32_e32 v27, 31, v26
	v_ashrrev_i32_e32 v41, 31, v40
	s_lshl_b64 s[68:69], s[76:77], 14
	v_lshlrev_b64 v[8:9], 11, v[8:9]
	v_lshlrev_b64 v[16:17], 11, v[16:17]
	v_lshlrev_b64 v[26:27], 11, v[26:27]
	v_lshlrev_b64 v[40:41], 11, v[40:41]
	v_lshl_add_u64 v[56:57], v[156:157], 0, s[68:69]
	v_lshl_add_u64 v[8:9], v[144:145], 0, v[8:9]
	global_load_dword v169, v[6:7], off
	global_load_dword v170, v[4:5], off
	s_nop 0
	global_load_dwordx4 v[4:7], v[8:9], off
	v_lshl_add_u64 v[12:13], v[48:49], 0, v[148:149]
	v_lshl_add_u64 v[20:21], v[144:145], 0, v[16:17]
	v_lshl_add_u64 v[24:25], v[48:49], 0, v[150:151]
	v_lshl_add_u64 v[28:29], v[144:145], 0, v[26:27]
	v_lshl_add_u64 v[36:37], v[48:49], 0, v[152:153]
	v_lshl_add_u64 v[44:45], v[144:145], 0, v[40:41]
	v_lshl_add_u64 v[48:49], v[48:49], 0, v[154:155]
	v_lshl_add_u64 v[52:53], v[56:57], 0, v[148:149]
	v_lshl_add_u64 v[56:57], v[56:57], 0, v[150:151]
	global_load_dwordx4 v[8:11], v[8:9], off offset:1024

.LBB0_1209:
	s_waitcnt lgkmcnt(0)
	s_barrier
	s_cmpk_eq_i32 s80, 0x780
	s_cbranch_scc1 .Lssd_pf_g3
	global_load_dwordx4 v[32:35], v[28:29], off
	s_nop 0
	global_load_dwordx4 v[28:31], v[28:29], off offset:1024
	s_nop 0
	global_load_dwordx4 v[36:39], v[36:37], off
	s_nop 0
	global_load_dwordx4 v[40:43], v[44:45], off
	s_nop 0
	global_load_dwordx4 v[44:47], v[44:45], off offset:1024
	s_nop 0
	global_load_dwordx4 v[48:51], v[48:49], off
	s_nop 0
	global_load_dwordx4 v[52:55], v[52:53], off
	s_nop 0
	global_load_dwordx4 v[56:59], v[56:57], off
